# sample attention: first-consumed V row loaded first, per-row counted waits in P.V
# speedup vs baseline: 1.0286x; 1.0023x over previous
.LBB0_49:
	s_or_b64 exec, exec, s[4:5]
	v_readlane_b32 s48, v250, 31
	v_readlane_b32 s60, v250, 43
	v_readlane_b32 s61, v250, 44
	s_add_u32 s4, s60, s16
	s_addc_u32 s5, s61, s17
	v_and_b32_e32 v125, 63, v101
	s_add_u32 s4, s4, s27
	v_ashrrev_i32_e32 v101, 31, v100
	s_addc_u32 s5, s5, 0
	v_lshlrev_b64 v[0:1], 12, v[100:101]
	v_lshl_add_u64 v[0:1], s[4:5], 0, v[0:1]
	v_lshlrev_b32_e32 v192, 4, v125
	v_lshl_add_u64 v[0:1], v[0:1], 0, v[192:193]
	global_load_dwordx4 v[128:131], v[0:1], off
	v_add_co_u32_e32 v2, vcc, s73, v0
	s_mov_b32 s4, 0xe000
	s_nop 0
	v_addc_co_u32_e32 v3, vcc, 0, v1, vcc
	global_load_dwordx4 v[120:123], v[2:3], off offset:-4096
	global_load_dwordx4 v[116:119], v[2:3], off
	v_add_co_u32_e32 v2, vcc, s72, v0
	v_lshlrev_b32_e32 v126, 5, v125
	s_nop 0
	v_addc_co_u32_e32 v3, vcc, 0, v1, vcc
	global_load_dwordx4 v[112:115], v[2:3], off offset:-4096
	global_load_dwordx4 v[108:111], v[2:3], off
	v_add_co_u32_e32 v2, vcc, s74, v0
	v_lshlrev_b32_e32 v127, 2, v124
	s_nop 0
	v_addc_co_u32_e32 v3, vcc, 0, v1, vcc
	global_load_dwordx4 v[104:107], v[2:3], off offset:-4096
	global_load_dwordx4 v[100:103], v[2:3], off
	v_add_co_u32_e32 v2, vcc, s77, v0
	v_add3_u32 v134, 0, v126, v127
	s_nop 0
	v_addc_co_u32_e32 v3, vcc, 0, v1, vcc
	global_load_dwordx4 v[96:99], v[2:3], off offset:-4096
	global_load_dwordx4 v[92:95], v[2:3], off
	v_add_co_u32_e32 v2, vcc, s79, v0
	s_add_i32 s25, s25, s70
	s_nop 0
	v_addc_co_u32_e32 v3, vcc, 0, v1, vcc
	global_load_dwordx4 v[88:91], v[2:3], off offset:-4096
	global_load_dwordx4 v[84:87], v[2:3], off
	v_add_co_u32_e32 v2, vcc, s81, v0
	s_add_i32 s23, s23, s30
	s_nop 0
	v_addc_co_u32_e32 v3, vcc, 0, v1, vcc
	global_load_dwordx4 v[80:83], v[2:3], off offset:-4096
	global_load_dwordx4 v[76:79], v[2:3], off
	v_add_co_u32_e32 v2, vcc, s4, v0
	s_mov_b32 s4, 0x10000
	s_nop 0
	v_addc_co_u32_e32 v3, vcc, 0, v1, vcc
	global_load_dwordx4 v[72:75], v[2:3], off offset:-4096
	global_load_dwordx4 v[68:71], v[2:3], off
	v_add_co_u32_e32 v2, vcc, s4, v0
	s_mov_b32 s4, 0x12000
	s_nop 0
	v_addc_co_u32_e32 v3, vcc, 0, v1, vcc
	global_load_dwordx4 v[64:67], v[2:3], off offset:-4096
	global_load_dwordx4 v[60:63], v[2:3], off
	v_add_co_u32_e32 v2, vcc, s4, v0
	s_mov_b32 s4, 0x14000
	s_nop 0
	v_addc_co_u32_e32 v3, vcc, 0, v1, vcc
	global_load_dwordx4 v[56:59], v[2:3], off offset:-4096
	global_load_dwordx4 v[52:55], v[2:3], off
	v_add_co_u32_e32 v2, vcc, s4, v0
	s_mov_b32 s4, 0x16000
	s_nop 0
	v_addc_co_u32_e32 v3, vcc, 0, v1, vcc
	global_load_dwordx4 v[48:51], v[2:3], off offset:-4096
	global_load_dwordx4 v[44:47], v[2:3], off
	v_add_co_u32_e32 v2, vcc, s4, v0
	s_mov_b32 s4, 0x18000
	s_nop 0
	v_addc_co_u32_e32 v3, vcc, 0, v1, vcc
	global_load_dwordx4 v[40:43], v[2:3], off offset:-4096
	global_load_dwordx4 v[36:39], v[2:3], off
	v_add_co_u32_e32 v2, vcc, s4, v0
	s_mov_b32 s4, 0x1a000
	s_nop 0
	v_addc_co_u32_e32 v3, vcc, 0, v1, vcc
	global_load_dwordx4 v[32:35], v[2:3], off offset:-4096
	global_load_dwordx4 v[28:31], v[2:3], off
	v_add_co_u32_e32 v2, vcc, s4, v0
	s_mov_b32 s4, 0x1c000
	s_nop 0
	v_addc_co_u32_e32 v3, vcc, 0, v1, vcc
	global_load_dwordx4 v[24:27], v[2:3], off offset:-4096
	global_load_dwordx4 v[20:23], v[2:3], off
	v_add_co_u32_e32 v2, vcc, s4, v0
	s_mov_b32 s4, 0x1e000
	s_nop 0
	v_addc_co_u32_e32 v3, vcc, 0, v1, vcc
	global_load_dwordx4 v[16:19], v[2:3], off offset:-4096
	global_load_dwordx4 v[12:15], v[2:3], off
	v_add_co_u32_e32 v2, vcc, s4, v0
	s_mov_b32 s4, 0x1f000
	s_nop 0
	v_addc_co_u32_e32 v3, vcc, 0, v1, vcc
	global_load_dwordx4 v[8:11], v[2:3], off offset:-4096
	global_load_dwordx4 v[4:7], v[2:3], off
	v_add_co_u32_e32 v2, vcc, s4, v0
	v_readlane_b32 s58, v250, 41
	s_nop 0
	v_addc_co_u32_e32 v3, vcc, 0, v1, vcc
	s_nop 0
	global_load_dwordx4 v[0:3], v[2:3], off
	s_waitcnt lgkmcnt(0)
	s_barrier
	ds_read2st64_b32 v[126:127], v134 offset1:8
	ds_read2st64_b32 v[132:133], v134 offset0:16 offset1:24
	v_cmp_lt_i32_e32 vcc, v219, v218
	v_readlane_b32 s59, v250, 42
	s_cmpk_gt_i32 s25, 0x1ff
	s_waitcnt lgkmcnt(1)
	v_max3_f32 v135, v126, s33, v127
	v_cndmask_b32_e32 v136, v217, v219, vcc
	s_waitcnt lgkmcnt(0)
	v_max3_f32 v135, v135, v132, v133
	v_lshlrev_b32_e32 v136, 2, v136
	ds_bpermute_b32 v137, v136, v135
	v_cmp_lt_i32_e32 vcc, v220, v218
	v_readlane_b32 s49, v250, 32
	v_readlane_b32 s50, v250, 33
	v_readlane_b32 s51, v250, 34
	s_waitcnt lgkmcnt(0)
	v_max_f32_e32 v137, v137, v137
	v_max_f32_e32 v135, v135, v137
	v_cndmask_b32_e32 v137, v217, v220, vcc
	v_lshlrev_b32_e32 v137, 2, v137
	ds_bpermute_b32 v138, v137, v135
	v_cmp_lt_i32_e32 vcc, v221, v218
	v_readlane_b32 s52, v250, 35
	v_readlane_b32 s53, v250, 36
	v_readlane_b32 s54, v250, 37
	s_waitcnt lgkmcnt(0)
	v_max_f32_e32 v138, v138, v138
	v_max_f32_e32 v135, v135, v138
	v_cndmask_b32_e32 v138, v217, v221, vcc
	v_lshlrev_b32_e32 v138, 2, v138
	ds_bpermute_b32 v139, v138, v135
	v_cmp_lt_i32_e32 vcc, v222, v218
	v_readlane_b32 s55, v250, 38
	v_readlane_b32 s56, v250, 39
	v_readlane_b32 s57, v250, 40
	s_waitcnt lgkmcnt(0)
	v_max_f32_e32 v139, v139, v139
	v_max_f32_e32 v135, v135, v139
	v_cndmask_b32_e32 v139, v217, v222, vcc
	v_lshlrev_b32_e32 v139, 2, v139
	ds_bpermute_b32 v140, v139, v135
	v_cmp_lt_i32_e32 vcc, v223, v218
	v_readlane_b32 s62, v250, 45
	v_readlane_b32 s63, v250, 46
	s_waitcnt lgkmcnt(0)
	v_max_f32_e32 v140, v140, v140
	v_max_f32_e32 v135, v135, v140
	v_cndmask_b32_e32 v140, v217, v223, vcc
	v_lshlrev_b32_e32 v140, 2, v140
	ds_bpermute_b32 v141, v140, v135
	v_cmp_lt_i32_e32 vcc, v224, v218
	s_waitcnt lgkmcnt(0)
	v_max_f32_e32 v141, v141, v141
	v_max_f32_e32 v135, v135, v141
	v_cndmask_b32_e32 v141, v217, v224, vcc
	v_lshlrev_b32_e32 v141, 2, v141
	ds_bpermute_b32 v142, v141, v135
	s_waitcnt lgkmcnt(0)
	v_max_f32_e32 v142, v142, v142
	v_max_f32_e32 v135, v135, v142
	v_sub_f32_e32 v126, v126, v135
	v_exp_f32_e32 v126, v126
	v_sub_f32_e32 v127, v127, v135
	v_exp_f32_e32 v127, v127
	v_sub_f32_e32 v132, v132, v135
	v_exp_f32_e32 v132, v132
	v_sub_f32_e32 v133, v133, v135
	v_exp_f32_e32 v133, v133
	v_add_f32_e32 v135, 0, v126
	v_add_f32_e32 v135, v127, v135
	v_add_f32_e32 v135, v132, v135
	v_add_f32_e32 v135, v133, v135
	ds_bpermute_b32 v136, v136, v135
	s_waitcnt lgkmcnt(0)
	v_add_f32_e32 v135, v135, v136
	ds_bpermute_b32 v136, v137, v135
	s_waitcnt lgkmcnt(0)
	v_add_f32_e32 v135, v135, v136
	ds_bpermute_b32 v136, v138, v135
	s_waitcnt lgkmcnt(0)
	v_add_f32_e32 v135, v135, v136
	ds_bpermute_b32 v136, v139, v135
	s_waitcnt lgkmcnt(0)
	v_add_f32_e32 v135, v135, v136
	ds_bpermute_b32 v136, v140, v135
	s_waitcnt lgkmcnt(0)
	v_add_f32_e32 v135, v135, v136
	ds_bpermute_b32 v136, v141, v135
	s_waitcnt lgkmcnt(0)
	v_add_f32_e32 v135, v135, v136
	v_div_scale_f32 v136, s[4:5], v135, v135, 1.0
	v_rcp_f32_e32 v137, v136
	s_mov_b64 s[4:5], s[42:43]
	v_fma_f32 v138, -v136, v137, 1.0
	v_fmac_f32_e32 v137, v138, v137
	v_div_scale_f32 v138, vcc, 1.0, v135, 1.0
	v_mul_f32_e32 v139, v138, v137
	v_fma_f32 v140, -v136, v139, v138
	v_fmac_f32_e32 v139, v140, v137
	v_fma_f32 v136, -v136, v139, v138
	v_div_fmas_f32 v136, v136, v137, v139
	v_div_fixup_f32 v135, v136, v135, 1.0
	v_mul_f32_e32 v126, v126, v135
	v_mul_f32_e32 v127, v127, v135
	ds_write2st64_b32 v134, v126, v127 offset1:8
	v_mul_f32_e32 v126, v132, v135
	v_mul_f32_e32 v127, v133, v135
	ds_write2st64_b32 v134, v126, v127 offset0:16 offset1:24
	v_lshl_add_u32 v126, v124, 10, 0
	s_waitcnt lgkmcnt(0)
	s_barrier
	ds_read_b128 v[132:135], v126
	ds_read_b128 v[136:139], v126 offset:16
	ds_read_b128 v[140:143], v126 offset:32
	ds_read_b128 v[144:147], v126 offset:48
	s_waitcnt vmcnt(31) lgkmcnt(3)
	v_pk_fma_f32 v[154:155], v[130:131], v[134:135], 0 op_sel_hi:[1,0,0]
	v_pk_fma_f32 v[156:157], v[128:129], v[134:135], 0 op_sel_hi:[1,0,0]
	v_mov_b32_e32 v134, v135
	s_waitcnt lgkmcnt(2)
	v_pk_fma_f32 v[166:167], v[130:131], v[138:139], 0 op_sel_hi:[1,0,0]
	v_pk_fma_f32 v[168:169], v[128:129], v[138:139], 0 op_sel_hi:[1,0,0]
	v_mov_b32_e32 v138, v139
	v_pk_fma_f32 v[148:149], v[130:131], v[132:133], 0 op_sel_hi:[1,0,0]
	v_pk_fma_f32 v[150:151], v[128:129], v[132:133], 0 op_sel_hi:[1,0,0]
	v_pk_fma_f32 v[152:153], v[130:131], v[132:133], 0 op_sel:[0,1,0] op_sel_hi:[1,1,0]
	v_pk_fma_f32 v[132:133], v[128:129], v[132:133], 0 op_sel:[0,1,0] op_sel_hi:[1,1,0]
	v_pk_fma_f32 v[158:159], v[130:131], v[134:135], 0 op_sel_hi:[1,0,0]
	v_pk_fma_f32 v[134:135], v[128:129], v[134:135], 0 op_sel_hi:[1,0,0]
	v_pk_fma_f32 v[160:161], v[130:131], v[136:137], 0 op_sel_hi:[1,0,0]
	v_pk_fma_f32 v[162:163], v[128:129], v[136:137], 0 op_sel_hi:[1,0,0]
	v_pk_fma_f32 v[164:165], v[130:131], v[136:137], 0 op_sel:[0,1,0] op_sel_hi:[1,1,0]
	v_pk_fma_f32 v[136:137], v[128:129], v[136:137], 0 op_sel:[0,1,0] op_sel_hi:[1,1,0]
	v_pk_fma_f32 v[170:171], v[130:131], v[138:139], 0 op_sel_hi:[1,0,0]
	v_pk_fma_f32 v[138:139], v[128:129], v[138:139], 0 op_sel_hi:[1,0,0]
	s_waitcnt lgkmcnt(1)
	v_mov_b32_e32 v128, v143
	s_waitcnt vmcnt(30)
	v_pk_fma_f32 v[150:151], v[120:121], v[140:141], v[150:151] op_sel_hi:[1,0,1]
	v_pk_fma_f32 v[148:149], v[122:123], v[140:141], v[148:149] op_sel_hi:[1,0,1]
	v_pk_fma_f32 v[132:133], v[120:121], v[140:141], v[132:133] op_sel:[0,1,0]
	v_pk_fma_f32 v[140:141], v[122:123], v[140:141], v[152:153] op_sel:[0,1,0]
	v_pk_fma_f32 v[152:153], v[120:121], v[142:143], v[156:157] op_sel_hi:[1,0,1]
	v_pk_fma_f32 v[154:155], v[122:123], v[142:143], v[154:155] op_sel_hi:[1,0,1]
	v_pk_fma_f32 v[134:135], v[120:121], v[128:129], v[134:135] op_sel_hi:[1,0,1]
	v_pk_fma_f32 v[142:143], v[122:123], v[128:129], v[158:159] op_sel_hi:[1,0,1]
	s_waitcnt lgkmcnt(0)
	v_pk_fma_f32 v[156:157], v[120:121], v[144:145], v[162:163] op_sel_hi:[1,0,1]
	v_pk_fma_f32 v[158:159], v[122:123], v[144:145], v[160:161] op_sel_hi:[1,0,1]
	v_pk_fma_f32 v[160:161], v[120:121], v[146:147], v[168:169] op_sel_hi:[1,0,1]
	v_pk_fma_f32 v[162:163], v[122:123], v[146:147], v[166:167] op_sel_hi:[1,0,1]
	ds_read_b128 v[128:131], v126 offset:64
	v_mov_b32_e32 v146, v147
	v_pk_fma_f32 v[136:137], v[120:121], v[144:145], v[136:137] op_sel:[0,1,0]
	v_pk_fma_f32 v[144:145], v[122:123], v[144:145], v[164:165] op_sel:[0,1,0]
	v_pk_fma_f32 v[138:139], v[120:121], v[146:147], v[138:139] op_sel_hi:[1,0,1]
	v_pk_fma_f32 v[146:147], v[122:123], v[146:147], v[170:171] op_sel_hi:[1,0,1]
	ds_read_b128 v[120:123], v126 offset:80
	s_waitcnt lgkmcnt(1)
	s_waitcnt vmcnt(29)
	v_pk_fma_f32 v[148:149], v[118:119], v[128:129], v[148:149] op_sel_hi:[1,0,1]
	v_pk_fma_f32 v[150:151], v[116:117], v[128:129], v[150:151] op_sel_hi:[1,0,1]
	v_pk_fma_f32 v[140:141], v[118:119], v[128:129], v[140:141] op_sel:[0,1,0]
	v_pk_fma_f32 v[132:133], v[116:117], v[128:129], v[132:133] op_sel:[0,1,0]
	v_mov_b32_e32 v128, v131
	v_pk_fma_f32 v[154:155], v[118:119], v[130:131], v[154:155] op_sel_hi:[1,0,1]
	v_pk_fma_f32 v[152:153], v[116:117], v[130:131], v[152:153] op_sel_hi:[1,0,1]
	v_pk_fma_f32 v[142:143], v[118:119], v[128:129], v[142:143] op_sel_hi:[1,0,1]
	v_pk_fma_f32 v[134:135], v[116:117], v[128:129], v[134:135] op_sel_hi:[1,0,1]
	s_waitcnt lgkmcnt(0)
	v_pk_fma_f32 v[158:159], v[118:119], v[120:121], v[158:159] op_sel_hi:[1,0,1]
	v_pk_fma_f32 v[156:157], v[116:117], v[120:121], v[156:157] op_sel_hi:[1,0,1]
	v_pk_fma_f32 v[144:145], v[118:119], v[120:121], v[144:145] op_sel:[0,1,0]
	v_pk_fma_f32 v[120:121], v[116:117], v[120:121], v[136:137] op_sel:[0,1,0]
	v_pk_fma_f32 v[136:137], v[118:119], v[122:123], v[162:163] op_sel_hi:[1,0,1]
	v_pk_fma_f32 v[160:161], v[116:117], v[122:123], v[160:161] op_sel_hi:[1,0,1]
	ds_read_b128 v[128:131], v126 offset:96
	v_mov_b32_e32 v122, v123
	v_pk_fma_f32 v[146:147], v[118:119], v[122:123], v[146:147] op_sel_hi:[1,0,1]
	v_pk_fma_f32 v[138:139], v[116:117], v[122:123], v[138:139] op_sel_hi:[1,0,1]
	ds_read_b128 v[116:119], v126 offset:112
	s_waitcnt lgkmcnt(1)
	v_mov_b32_e32 v122, v131
	s_waitcnt vmcnt(28)
	v_pk_fma_f32 v[148:149], v[114:115], v[128:129], v[148:149] op_sel_hi:[1,0,1]
	v_pk_fma_f32 v[150:151], v[112:113], v[128:129], v[150:151] op_sel_hi:[1,0,1]
	v_pk_fma_f32 v[140:141], v[114:115], v[128:129], v[140:141] op_sel:[0,1,0]
	v_pk_fma_f32 v[128:129], v[112:113], v[128:129], v[132:133] op_sel:[0,1,0]
	v_pk_fma_f32 v[132:133], v[114:115], v[130:131], v[154:155] op_sel_hi:[1,0,1]
	v_pk_fma_f32 v[152:153], v[112:113], v[130:131], v[152:153] op_sel_hi:[1,0,1]
	v_pk_fma_f32 v[130:131], v[114:115], v[122:123], v[142:143] op_sel_hi:[1,0,1]
	v_pk_fma_f32 v[134:135], v[112:113], v[122:123], v[134:135] op_sel_hi:[1,0,1]
	s_waitcnt lgkmcnt(0)
	v_pk_fma_f32 v[142:143], v[114:115], v[116:117], v[158:159] op_sel_hi:[1,0,1]
	v_pk_fma_f32 v[154:155], v[112:113], v[116:117], v[156:157] op_sel_hi:[1,0,1]
	v_pk_fma_f32 v[144:145], v[114:115], v[116:117], v[144:145] op_sel:[0,1,0]
	v_pk_fma_f32 v[116:117], v[112:113], v[116:117], v[120:121] op_sel:[0,1,0]
	v_pk_fma_f32 v[136:137], v[114:115], v[118:119], v[136:137] op_sel_hi:[1,0,1]
	v_pk_fma_f32 v[156:157], v[112:113], v[118:119], v[160:161] op_sel_hi:[1,0,1]
	ds_read_b128 v[120:123], v126 offset:128
	v_mov_b32_e32 v118, v119
	v_pk_fma_f32 v[146:147], v[114:115], v[118:119], v[146:147] op_sel_hi:[1,0,1]
	v_pk_fma_f32 v[138:139], v[112:113], v[118:119], v[138:139] op_sel_hi:[1,0,1]
	ds_read_b128 v[112:115], v126 offset:144
	s_waitcnt lgkmcnt(1)
	v_mov_b32_e32 v118, v123
	s_waitcnt vmcnt(27)
	v_pk_fma_f32 v[148:149], v[110:111], v[120:121], v[148:149] op_sel_hi:[1,0,1]
	v_pk_fma_f32 v[150:151], v[108:109], v[120:121], v[150:151] op_sel_hi:[1,0,1]
	v_pk_fma_f32 v[140:141], v[110:111], v[120:121], v[140:141] op_sel:[0,1,0]
	v_pk_fma_f32 v[120:121], v[108:109], v[120:121], v[128:129] op_sel:[0,1,0]
	v_pk_fma_f32 v[128:129], v[110:111], v[122:123], v[132:133] op_sel_hi:[1,0,1]
	v_pk_fma_f32 v[132:133], v[108:109], v[122:123], v[152:153] op_sel_hi:[1,0,1]
	v_pk_fma_f32 v[122:123], v[110:111], v[118:119], v[130:131] op_sel_hi:[1,0,1]
	v_pk_fma_f32 v[130:131], v[108:109], v[118:119], v[134:135] op_sel_hi:[1,0,1]
	s_waitcnt lgkmcnt(0)
	v_pk_fma_f32 v[134:135], v[110:111], v[112:113], v[142:143] op_sel_hi:[1,0,1]
	v_pk_fma_f32 v[142:143], v[108:109], v[112:113], v[154:155] op_sel_hi:[1,0,1]
	v_pk_fma_f32 v[144:145], v[110:111], v[112:113], v[144:145] op_sel:[0,1,0]
	v_pk_fma_f32 v[112:113], v[108:109], v[112:113], v[116:117] op_sel:[0,1,0]
	v_pk_fma_f32 v[136:137], v[110:111], v[114:115], v[136:137] op_sel_hi:[1,0,1]
	v_pk_fma_f32 v[152:153], v[108:109], v[114:115], v[156:157] op_sel_hi:[1,0,1]
	ds_read_b128 v[116:119], v126 offset:160
	v_mov_b32_e32 v114, v115
	v_pk_fma_f32 v[146:147], v[110:111], v[114:115], v[146:147] op_sel_hi:[1,0,1]
	v_pk_fma_f32 v[138:139], v[108:109], v[114:115], v[138:139] op_sel_hi:[1,0,1]
	ds_read_b128 v[108:111], v126 offset:176
	s_waitcnt lgkmcnt(1)
	v_mov_b32_e32 v114, v119
	s_waitcnt vmcnt(26)
	v_pk_fma_f32 v[148:149], v[106:107], v[116:117], v[148:149] op_sel_hi:[1,0,1]
	v_pk_fma_f32 v[150:151], v[104:105], v[116:117], v[150:151] op_sel_hi:[1,0,1]
	v_pk_fma_f32 v[140:141], v[106:107], v[116:117], v[140:141] op_sel:[0,1,0]
	v_pk_fma_f32 v[116:117], v[104:105], v[116:117], v[120:121] op_sel:[0,1,0]
	v_pk_fma_f32 v[120:121], v[106:107], v[118:119], v[128:129] op_sel_hi:[1,0,1]
	v_pk_fma_f32 v[128:129], v[104:105], v[118:119], v[132:133] op_sel_hi:[1,0,1]
	v_pk_fma_f32 v[118:119], v[106:107], v[114:115], v[122:123] op_sel_hi:[1,0,1]
	v_pk_fma_f32 v[122:123], v[104:105], v[114:115], v[130:131] op_sel_hi:[1,0,1]
	s_waitcnt lgkmcnt(0)
	v_pk_fma_f32 v[130:131], v[106:107], v[108:109], v[134:135] op_sel_hi:[1,0,1]
	v_pk_fma_f32 v[132:133], v[104:105], v[108:109], v[142:143] op_sel_hi:[1,0,1]
	v_pk_fma_f32 v[134:135], v[106:107], v[108:109], v[144:145] op_sel:[0,1,0]
	v_pk_fma_f32 v[108:109], v[104:105], v[108:109], v[112:113] op_sel:[0,1,0]
	v_pk_fma_f32 v[136:137], v[106:107], v[110:111], v[136:137] op_sel_hi:[1,0,1]
	v_pk_fma_f32 v[142:143], v[104:105], v[110:111], v[152:153] op_sel_hi:[1,0,1]
	ds_read_b128 v[112:115], v126 offset:192
	v_mov_b32_e32 v110, v111
	v_pk_fma_f32 v[144:145], v[106:107], v[110:111], v[146:147] op_sel_hi:[1,0,1]
	v_pk_fma_f32 v[138:139], v[104:105], v[110:111], v[138:139] op_sel_hi:[1,0,1]
	ds_read_b128 v[104:107], v126 offset:208
	s_waitcnt lgkmcnt(1)
	v_mov_b32_e32 v110, v115
	s_waitcnt vmcnt(25)
	v_pk_fma_f32 v[146:147], v[102:103], v[112:113], v[148:149] op_sel_hi:[1,0,1]
	v_pk_fma_f32 v[148:149], v[100:101], v[112:113], v[150:151] op_sel_hi:[1,0,1]
	v_pk_fma_f32 v[140:141], v[102:103], v[112:113], v[140:141] op_sel:[0,1,0]
	v_pk_fma_f32 v[112:113], v[100:101], v[112:113], v[116:117] op_sel:[0,1,0]
	v_pk_fma_f32 v[116:117], v[102:103], v[114:115], v[120:121] op_sel_hi:[1,0,1]
	v_pk_fma_f32 v[120:121], v[100:101], v[114:115], v[128:129] op_sel_hi:[1,0,1]
	v_pk_fma_f32 v[114:115], v[102:103], v[110:111], v[118:119] op_sel_hi:[1,0,1]
	v_pk_fma_f32 v[118:119], v[100:101], v[110:111], v[122:123] op_sel_hi:[1,0,1]
	s_waitcnt lgkmcnt(0)
	v_pk_fma_f32 v[122:123], v[102:103], v[104:105], v[130:131] op_sel_hi:[1,0,1]
	v_pk_fma_f32 v[128:129], v[100:101], v[104:105], v[132:133] op_sel_hi:[1,0,1]
	v_pk_fma_f32 v[130:131], v[102:103], v[104:105], v[134:135] op_sel:[0,1,0]
	v_pk_fma_f32 v[104:105], v[100:101], v[104:105], v[108:109] op_sel:[0,1,0]
	v_pk_fma_f32 v[132:133], v[102:103], v[106:107], v[136:137] op_sel_hi:[1,0,1]
	v_pk_fma_f32 v[134:135], v[100:101], v[106:107], v[142:143] op_sel_hi:[1,0,1]
	ds_read_b128 v[108:111], v126 offset:224
	v_mov_b32_e32 v106, v107
	v_pk_fma_f32 v[136:137], v[102:103], v[106:107], v[144:145] op_sel_hi:[1,0,1]
	v_pk_fma_f32 v[138:139], v[100:101], v[106:107], v[138:139] op_sel_hi:[1,0,1]
	ds_read_b128 v[100:103], v126 offset:240
	s_waitcnt lgkmcnt(1)
	v_mov_b32_e32 v106, v111
	s_waitcnt vmcnt(24)
	v_pk_fma_f32 v[142:143], v[98:99], v[108:109], v[146:147] op_sel_hi:[1,0,1]
	v_pk_fma_f32 v[144:145], v[96:97], v[108:109], v[148:149] op_sel_hi:[1,0,1]
	v_pk_fma_f32 v[140:141], v[98:99], v[108:109], v[140:141] op_sel:[0,1,0]
	v_pk_fma_f32 v[108:109], v[96:97], v[108:109], v[112:113] op_sel:[0,1,0]
	v_pk_fma_f32 v[112:113], v[98:99], v[110:111], v[116:117] op_sel_hi:[1,0,1]
	v_pk_fma_f32 v[116:117], v[96:97], v[110:111], v[120:121] op_sel_hi:[1,0,1]
	v_pk_fma_f32 v[110:111], v[98:99], v[106:107], v[114:115] op_sel_hi:[1,0,1]
	v_pk_fma_f32 v[114:115], v[96:97], v[106:107], v[118:119] op_sel_hi:[1,0,1]
	s_waitcnt lgkmcnt(0)
	v_pk_fma_f32 v[118:119], v[98:99], v[100:101], v[122:123] op_sel_hi:[1,0,1]
	v_pk_fma_f32 v[120:121], v[96:97], v[100:101], v[128:129] op_sel_hi:[1,0,1]
	v_pk_fma_f32 v[122:123], v[98:99], v[100:101], v[130:131] op_sel:[0,1,0]
	v_pk_fma_f32 v[100:101], v[96:97], v[100:101], v[104:105] op_sel:[0,1,0]
	v_pk_fma_f32 v[128:129], v[98:99], v[102:103], v[132:133] op_sel_hi:[1,0,1]
	v_pk_fma_f32 v[130:131], v[96:97], v[102:103], v[134:135] op_sel_hi:[1,0,1]
	ds_read_b128 v[104:107], v126 offset:256
	v_mov_b32_e32 v102, v103
	v_pk_fma_f32 v[132:133], v[98:99], v[102:103], v[136:137] op_sel_hi:[1,0,1]
	v_pk_fma_f32 v[134:135], v[96:97], v[102:103], v[138:139] op_sel_hi:[1,0,1]
	ds_read_b128 v[96:99], v126 offset:272
	s_waitcnt lgkmcnt(1)
	v_mov_b32_e32 v102, v107
	s_waitcnt vmcnt(23)
	v_pk_fma_f32 v[136:137], v[94:95], v[104:105], v[142:143] op_sel_hi:[1,0,1]
	v_pk_fma_f32 v[138:139], v[92:93], v[104:105], v[144:145] op_sel_hi:[1,0,1]
	v_pk_fma_f32 v[140:141], v[94:95], v[104:105], v[140:141] op_sel:[0,1,0]
	v_pk_fma_f32 v[104:105], v[92:93], v[104:105], v[108:109] op_sel:[0,1,0]
	v_pk_fma_f32 v[108:109], v[94:95], v[106:107], v[112:113] op_sel_hi:[1,0,1]
	v_pk_fma_f32 v[112:113], v[92:93], v[106:107], v[116:117] op_sel_hi:[1,0,1]
	v_pk_fma_f32 v[106:107], v[94:95], v[102:103], v[110:111] op_sel_hi:[1,0,1]
	v_pk_fma_f32 v[110:111], v[92:93], v[102:103], v[114:115] op_sel_hi:[1,0,1]
	s_waitcnt lgkmcnt(0)
	v_pk_fma_f32 v[114:115], v[94:95], v[96:97], v[118:119] op_sel_hi:[1,0,1]
	v_pk_fma_f32 v[116:117], v[92:93], v[96:97], v[120:121] op_sel_hi:[1,0,1]
	v_pk_fma_f32 v[118:119], v[94:95], v[96:97], v[122:123] op_sel:[0,1,0]
	v_pk_fma_f32 v[96:97], v[92:93], v[96:97], v[100:101] op_sel:[0,1,0]
	v_pk_fma_f32 v[120:121], v[94:95], v[98:99], v[128:129] op_sel_hi:[1,0,1]
	v_pk_fma_f32 v[122:123], v[92:93], v[98:99], v[130:131] op_sel_hi:[1,0,1]
	ds_read_b128 v[100:103], v126 offset:288
	v_mov_b32_e32 v98, v99
	v_pk_fma_f32 v[128:129], v[94:95], v[98:99], v[132:133] op_sel_hi:[1,0,1]
	v_pk_fma_f32 v[130:131], v[92:93], v[98:99], v[134:135] op_sel_hi:[1,0,1]
	ds_read_b128 v[92:95], v126 offset:304
	s_waitcnt lgkmcnt(1)
	v_mov_b32_e32 v98, v103
	s_waitcnt vmcnt(22)
	v_pk_fma_f32 v[132:133], v[90:91], v[100:101], v[136:137] op_sel_hi:[1,0,1]
	v_pk_fma_f32 v[134:135], v[88:89], v[100:101], v[138:139] op_sel_hi:[1,0,1]
	v_pk_fma_f32 v[136:137], v[90:91], v[100:101], v[140:141] op_sel:[0,1,0]
	v_pk_fma_f32 v[100:101], v[88:89], v[100:101], v[104:105] op_sel:[0,1,0]
	v_pk_fma_f32 v[104:105], v[90:91], v[102:103], v[108:109] op_sel_hi:[1,0,1]
	v_pk_fma_f32 v[108:109], v[88:89], v[102:103], v[112:113] op_sel_hi:[1,0,1]
	v_pk_fma_f32 v[102:103], v[90:91], v[98:99], v[106:107] op_sel_hi:[1,0,1]
	v_pk_fma_f32 v[106:107], v[88:89], v[98:99], v[110:111] op_sel_hi:[1,0,1]
	s_waitcnt lgkmcnt(0)
	v_pk_fma_f32 v[110:111], v[90:91], v[92:93], v[114:115] op_sel_hi:[1,0,1]
	v_pk_fma_f32 v[112:113], v[88:89], v[92:93], v[116:117] op_sel_hi:[1,0,1]
	v_pk_fma_f32 v[114:115], v[90:91], v[92:93], v[118:119] op_sel:[0,1,0]
	v_pk_fma_f32 v[92:93], v[88:89], v[92:93], v[96:97] op_sel:[0,1,0]
	v_pk_fma_f32 v[116:117], v[90:91], v[94:95], v[120:121] op_sel_hi:[1,0,1]
	v_pk_fma_f32 v[118:119], v[88:89], v[94:95], v[122:123] op_sel_hi:[1,0,1]
	ds_read_b128 v[96:99], v126 offset:320
	v_mov_b32_e32 v94, v95
	v_pk_fma_f32 v[120:121], v[90:91], v[94:95], v[128:129] op_sel_hi:[1,0,1]
	v_pk_fma_f32 v[122:123], v[88:89], v[94:95], v[130:131] op_sel_hi:[1,0,1]
	ds_read_b128 v[88:91], v126 offset:336
	s_waitcnt lgkmcnt(1)
	v_mov_b32_e32 v94, v99
	s_waitcnt vmcnt(21)
	v_pk_fma_f32 v[128:129], v[86:87], v[96:97], v[132:133] op_sel_hi:[1,0,1]
	v_pk_fma_f32 v[130:131], v[84:85], v[96:97], v[134:135] op_sel_hi:[1,0,1]
	v_pk_fma_f32 v[132:133], v[86:87], v[96:97], v[136:137] op_sel:[0,1,0]
	v_pk_fma_f32 v[96:97], v[84:85], v[96:97], v[100:101] op_sel:[0,1,0]
	v_pk_fma_f32 v[100:101], v[86:87], v[98:99], v[104:105] op_sel_hi:[1,0,1]
	v_pk_fma_f32 v[104:105], v[84:85], v[98:99], v[108:109] op_sel_hi:[1,0,1]
	v_pk_fma_f32 v[98:99], v[86:87], v[94:95], v[102:103] op_sel_hi:[1,0,1]
	v_pk_fma_f32 v[102:103], v[84:85], v[94:95], v[106:107] op_sel_hi:[1,0,1]
	s_waitcnt lgkmcnt(0)
	v_pk_fma_f32 v[106:107], v[86:87], v[88:89], v[110:111] op_sel_hi:[1,0,1]
	v_pk_fma_f32 v[108:109], v[84:85], v[88:89], v[112:113] op_sel_hi:[1,0,1]
	v_pk_fma_f32 v[110:111], v[86:87], v[88:89], v[114:115] op_sel:[0,1,0]
	v_pk_fma_f32 v[88:89], v[84:85], v[88:89], v[92:93] op_sel:[0,1,0]
	v_pk_fma_f32 v[112:113], v[86:87], v[90:91], v[116:117] op_sel_hi:[1,0,1]
	v_pk_fma_f32 v[114:115], v[84:85], v[90:91], v[118:119] op_sel_hi:[1,0,1]
	ds_read_b128 v[92:95], v126 offset:352
	v_mov_b32_e32 v90, v91
	v_pk_fma_f32 v[116:117], v[86:87], v[90:91], v[120:121] op_sel_hi:[1,0,1]
	v_pk_fma_f32 v[118:119], v[84:85], v[90:91], v[122:123] op_sel_hi:[1,0,1]
	ds_read_b128 v[84:87], v126 offset:368
	s_waitcnt lgkmcnt(1)
	v_mov_b32_e32 v90, v95
	s_waitcnt vmcnt(20)
	v_pk_fma_f32 v[120:121], v[82:83], v[92:93], v[128:129] op_sel_hi:[1,0,1]
	v_pk_fma_f32 v[122:123], v[80:81], v[92:93], v[130:131] op_sel_hi:[1,0,1]
	v_pk_fma_f32 v[128:129], v[82:83], v[92:93], v[132:133] op_sel:[0,1,0]
	v_pk_fma_f32 v[92:93], v[80:81], v[92:93], v[96:97] op_sel:[0,1,0]
	v_pk_fma_f32 v[96:97], v[82:83], v[94:95], v[100:101] op_sel_hi:[1,0,1]
	v_pk_fma_f32 v[100:101], v[80:81], v[94:95], v[104:105] op_sel_hi:[1,0,1]
	v_pk_fma_f32 v[94:95], v[82:83], v[90:91], v[98:99] op_sel_hi:[1,0,1]
	v_pk_fma_f32 v[98:99], v[80:81], v[90:91], v[102:103] op_sel_hi:[1,0,1]
	s_waitcnt lgkmcnt(0)
	v_pk_fma_f32 v[102:103], v[82:83], v[84:85], v[106:107] op_sel_hi:[1,0,1]
	v_pk_fma_f32 v[104:105], v[80:81], v[84:85], v[108:109] op_sel_hi:[1,0,1]
	v_pk_fma_f32 v[106:107], v[82:83], v[84:85], v[110:111] op_sel:[0,1,0]
	v_pk_fma_f32 v[84:85], v[80:81], v[84:85], v[88:89] op_sel:[0,1,0]
	v_pk_fma_f32 v[108:109], v[82:83], v[86:87], v[112:113] op_sel_hi:[1,0,1]
	v_pk_fma_f32 v[110:111], v[80:81], v[86:87], v[114:115] op_sel_hi:[1,0,1]
	ds_read_b128 v[88:91], v126 offset:384
	v_mov_b32_e32 v86, v87
	v_pk_fma_f32 v[112:113], v[82:83], v[86:87], v[116:117] op_sel_hi:[1,0,1]
	v_pk_fma_f32 v[114:115], v[80:81], v[86:87], v[118:119] op_sel_hi:[1,0,1]
	ds_read_b128 v[80:83], v126 offset:400
	s_waitcnt lgkmcnt(1)
	v_mov_b32_e32 v86, v91
	s_waitcnt vmcnt(19)
	v_pk_fma_f32 v[116:117], v[78:79], v[88:89], v[120:121] op_sel_hi:[1,0,1]
	v_pk_fma_f32 v[118:119], v[76:77], v[88:89], v[122:123] op_sel_hi:[1,0,1]
	v_pk_fma_f32 v[120:121], v[78:79], v[88:89], v[128:129] op_sel:[0,1,0]
	v_pk_fma_f32 v[88:89], v[76:77], v[88:89], v[92:93] op_sel:[0,1,0]
	v_pk_fma_f32 v[92:93], v[78:79], v[90:91], v[96:97] op_sel_hi:[1,0,1]
	v_pk_fma_f32 v[96:97], v[76:77], v[90:91], v[100:101] op_sel_hi:[1,0,1]
	v_pk_fma_f32 v[90:91], v[78:79], v[86:87], v[94:95] op_sel_hi:[1,0,1]
	v_pk_fma_f32 v[94:95], v[76:77], v[86:87], v[98:99] op_sel_hi:[1,0,1]
	s_waitcnt lgkmcnt(0)
	v_pk_fma_f32 v[98:99], v[78:79], v[80:81], v[102:103] op_sel_hi:[1,0,1]
	v_pk_fma_f32 v[100:101], v[76:77], v[80:81], v[104:105] op_sel_hi:[1,0,1]
	v_pk_fma_f32 v[102:103], v[78:79], v[80:81], v[106:107] op_sel:[0,1,0]
	v_pk_fma_f32 v[80:81], v[76:77], v[80:81], v[84:85] op_sel:[0,1,0]
	v_pk_fma_f32 v[104:105], v[78:79], v[82:83], v[108:109] op_sel_hi:[1,0,1]
	v_pk_fma_f32 v[106:107], v[76:77], v[82:83], v[110:111] op_sel_hi:[1,0,1]
	ds_read_b128 v[84:87], v126 offset:416
	v_mov_b32_e32 v82, v83
	v_pk_fma_f32 v[108:109], v[78:79], v[82:83], v[112:113] op_sel_hi:[1,0,1]
	v_pk_fma_f32 v[110:111], v[76:77], v[82:83], v[114:115] op_sel_hi:[1,0,1]
	ds_read_b128 v[76:79], v126 offset:432
	s_waitcnt lgkmcnt(1)
	v_mov_b32_e32 v82, v87
	s_waitcnt vmcnt(18)
	v_pk_fma_f32 v[112:113], v[74:75], v[84:85], v[116:117] op_sel_hi:[1,0,1]
	v_pk_fma_f32 v[114:115], v[72:73], v[84:85], v[118:119] op_sel_hi:[1,0,1]
	v_pk_fma_f32 v[116:117], v[74:75], v[84:85], v[120:121] op_sel:[0,1,0]
	v_pk_fma_f32 v[84:85], v[72:73], v[84:85], v[88:89] op_sel:[0,1,0]
	v_pk_fma_f32 v[88:89], v[74:75], v[86:87], v[92:93] op_sel_hi:[1,0,1]
	v_pk_fma_f32 v[92:93], v[72:73], v[86:87], v[96:97] op_sel_hi:[1,0,1]
	v_pk_fma_f32 v[86:87], v[74:75], v[82:83], v[90:91] op_sel_hi:[1,0,1]
	v_pk_fma_f32 v[90:91], v[72:73], v[82:83], v[94:95] op_sel_hi:[1,0,1]
	s_waitcnt lgkmcnt(0)
	v_pk_fma_f32 v[94:95], v[74:75], v[76:77], v[98:99] op_sel_hi:[1,0,1]
	v_pk_fma_f32 v[96:97], v[72:73], v[76:77], v[100:101] op_sel_hi:[1,0,1]
	v_pk_fma_f32 v[98:99], v[74:75], v[76:77], v[102:103] op_sel:[0,1,0]
	v_pk_fma_f32 v[76:77], v[72:73], v[76:77], v[80:81] op_sel:[0,1,0]
	v_pk_fma_f32 v[100:101], v[74:75], v[78:79], v[104:105] op_sel_hi:[1,0,1]
	v_pk_fma_f32 v[102:103], v[72:73], v[78:79], v[106:107] op_sel_hi:[1,0,1]
	ds_read_b128 v[80:83], v126 offset:448
	v_mov_b32_e32 v78, v79
	v_pk_fma_f32 v[104:105], v[74:75], v[78:79], v[108:109] op_sel_hi:[1,0,1]
	v_pk_fma_f32 v[106:107], v[72:73], v[78:79], v[110:111] op_sel_hi:[1,0,1]
	ds_read_b128 v[72:75], v126 offset:464
	s_waitcnt lgkmcnt(1)
	v_mov_b32_e32 v78, v83
	s_waitcnt vmcnt(17)
	v_pk_fma_f32 v[108:109], v[70:71], v[80:81], v[112:113] op_sel_hi:[1,0,1]
	v_pk_fma_f32 v[110:111], v[68:69], v[80:81], v[114:115] op_sel_hi:[1,0,1]
	v_pk_fma_f32 v[112:113], v[70:71], v[80:81], v[116:117] op_sel:[0,1,0]
	v_pk_fma_f32 v[80:81], v[68:69], v[80:81], v[84:85] op_sel:[0,1,0]
	v_pk_fma_f32 v[84:85], v[70:71], v[82:83], v[88:89] op_sel_hi:[1,0,1]
	v_pk_fma_f32 v[88:89], v[68:69], v[82:83], v[92:93] op_sel_hi:[1,0,1]
	v_pk_fma_f32 v[82:83], v[70:71], v[78:79], v[86:87] op_sel_hi:[1,0,1]
	v_pk_fma_f32 v[86:87], v[68:69], v[78:79], v[90:91] op_sel_hi:[1,0,1]
	s_waitcnt lgkmcnt(0)
	v_pk_fma_f32 v[90:91], v[70:71], v[72:73], v[94:95] op_sel_hi:[1,0,1]
	v_pk_fma_f32 v[92:93], v[68:69], v[72:73], v[96:97] op_sel_hi:[1,0,1]
	v_pk_fma_f32 v[94:95], v[70:71], v[72:73], v[98:99] op_sel:[0,1,0]
	v_pk_fma_f32 v[72:73], v[68:69], v[72:73], v[76:77] op_sel:[0,1,0]
	v_pk_fma_f32 v[96:97], v[70:71], v[74:75], v[100:101] op_sel_hi:[1,0,1]
	v_pk_fma_f32 v[98:99], v[68:69], v[74:75], v[102:103] op_sel_hi:[1,0,1]
	ds_read_b128 v[76:79], v126 offset:480
	v_mov_b32_e32 v74, v75
	v_pk_fma_f32 v[100:101], v[70:71], v[74:75], v[104:105] op_sel_hi:[1,0,1]
	v_pk_fma_f32 v[102:103], v[68:69], v[74:75], v[106:107] op_sel_hi:[1,0,1]
	ds_read_b128 v[68:71], v126 offset:496
	s_waitcnt lgkmcnt(1)
	v_mov_b32_e32 v74, v79
	s_waitcnt vmcnt(16)
	v_pk_fma_f32 v[104:105], v[66:67], v[76:77], v[108:109] op_sel_hi:[1,0,1]
	v_pk_fma_f32 v[106:107], v[64:65], v[76:77], v[110:111] op_sel_hi:[1,0,1]
	v_pk_fma_f32 v[108:109], v[66:67], v[76:77], v[112:113] op_sel:[0,1,0]
	v_pk_fma_f32 v[76:77], v[64:65], v[76:77], v[80:81] op_sel:[0,1,0]
	v_pk_fma_f32 v[80:81], v[66:67], v[78:79], v[84:85] op_sel_hi:[1,0,1]
	v_pk_fma_f32 v[84:85], v[64:65], v[78:79], v[88:89] op_sel_hi:[1,0,1]
	v_pk_fma_f32 v[78:79], v[66:67], v[74:75], v[82:83] op_sel_hi:[1,0,1]
	v_pk_fma_f32 v[82:83], v[64:65], v[74:75], v[86:87] op_sel_hi:[1,0,1]
	s_waitcnt lgkmcnt(0)
	v_pk_fma_f32 v[86:87], v[66:67], v[68:69], v[90:91] op_sel_hi:[1,0,1]
	v_pk_fma_f32 v[88:89], v[64:65], v[68:69], v[92:93] op_sel_hi:[1,0,1]
	v_pk_fma_f32 v[90:91], v[66:67], v[68:69], v[94:95] op_sel:[0,1,0]
	v_pk_fma_f32 v[68:69], v[64:65], v[68:69], v[72:73] op_sel:[0,1,0]
	v_pk_fma_f32 v[92:93], v[66:67], v[70:71], v[96:97] op_sel_hi:[1,0,1]
	v_pk_fma_f32 v[94:95], v[64:65], v[70:71], v[98:99] op_sel_hi:[1,0,1]
	ds_read_b128 v[72:75], v126 offset:512
	v_mov_b32_e32 v70, v71
	v_pk_fma_f32 v[96:97], v[66:67], v[70:71], v[100:101] op_sel_hi:[1,0,1]
	v_pk_fma_f32 v[98:99], v[64:65], v[70:71], v[102:103] op_sel_hi:[1,0,1]
	ds_read_b128 v[64:67], v126 offset:528
	s_waitcnt lgkmcnt(1)
	v_mov_b32_e32 v70, v75
	s_waitcnt vmcnt(15)
	v_pk_fma_f32 v[100:101], v[62:63], v[72:73], v[104:105] op_sel_hi:[1,0,1]
	v_pk_fma_f32 v[102:103], v[60:61], v[72:73], v[106:107] op_sel_hi:[1,0,1]
	v_pk_fma_f32 v[104:105], v[62:63], v[72:73], v[108:109] op_sel:[0,1,0]
	v_pk_fma_f32 v[72:73], v[60:61], v[72:73], v[76:77] op_sel:[0,1,0]
	v_pk_fma_f32 v[76:77], v[62:63], v[74:75], v[80:81] op_sel_hi:[1,0,1]
	v_pk_fma_f32 v[80:81], v[60:61], v[74:75], v[84:85] op_sel_hi:[1,0,1]
	v_pk_fma_f32 v[74:75], v[62:63], v[70:71], v[78:79] op_sel_hi:[1,0,1]
	v_pk_fma_f32 v[78:79], v[60:61], v[70:71], v[82:83] op_sel_hi:[1,0,1]
	s_waitcnt lgkmcnt(0)
	v_pk_fma_f32 v[82:83], v[62:63], v[64:65], v[86:87] op_sel_hi:[1,0,1]
	v_pk_fma_f32 v[84:85], v[60:61], v[64:65], v[88:89] op_sel_hi:[1,0,1]
	v_pk_fma_f32 v[86:87], v[62:63], v[64:65], v[90:91] op_sel:[0,1,0]
	v_pk_fma_f32 v[64:65], v[60:61], v[64:65], v[68:69] op_sel:[0,1,0]
	v_pk_fma_f32 v[88:89], v[62:63], v[66:67], v[92:93] op_sel_hi:[1,0,1]
	v_pk_fma_f32 v[90:91], v[60:61], v[66:67], v[94:95] op_sel_hi:[1,0,1]
	ds_read_b128 v[68:71], v126 offset:544
	v_mov_b32_e32 v66, v67
	v_pk_fma_f32 v[92:93], v[62:63], v[66:67], v[96:97] op_sel_hi:[1,0,1]
	v_pk_fma_f32 v[94:95], v[60:61], v[66:67], v[98:99] op_sel_hi:[1,0,1]
	ds_read_b128 v[60:63], v126 offset:560
	s_waitcnt lgkmcnt(1)
	v_mov_b32_e32 v66, v71
	s_waitcnt vmcnt(14)
	v_pk_fma_f32 v[96:97], v[58:59], v[68:69], v[100:101] op_sel_hi:[1,0,1]
	v_pk_fma_f32 v[98:99], v[56:57], v[68:69], v[102:103] op_sel_hi:[1,0,1]
	v_pk_fma_f32 v[100:101], v[58:59], v[68:69], v[104:105] op_sel:[0,1,0]
	v_pk_fma_f32 v[68:69], v[56:57], v[68:69], v[72:73] op_sel:[0,1,0]
	v_pk_fma_f32 v[72:73], v[58:59], v[70:71], v[76:77] op_sel_hi:[1,0,1]
	v_pk_fma_f32 v[76:77], v[56:57], v[70:71], v[80:81] op_sel_hi:[1,0,1]
	v_pk_fma_f32 v[70:71], v[58:59], v[66:67], v[74:75] op_sel_hi:[1,0,1]
	v_pk_fma_f32 v[74:75], v[56:57], v[66:67], v[78:79] op_sel_hi:[1,0,1]
	s_waitcnt lgkmcnt(0)
	v_pk_fma_f32 v[78:79], v[58:59], v[60:61], v[82:83] op_sel_hi:[1,0,1]
	v_pk_fma_f32 v[80:81], v[56:57], v[60:61], v[84:85] op_sel_hi:[1,0,1]
	v_pk_fma_f32 v[82:83], v[58:59], v[60:61], v[86:87] op_sel:[0,1,0]
	v_pk_fma_f32 v[60:61], v[56:57], v[60:61], v[64:65] op_sel:[0,1,0]
	v_pk_fma_f32 v[84:85], v[58:59], v[62:63], v[88:89] op_sel_hi:[1,0,1]
	v_pk_fma_f32 v[86:87], v[56:57], v[62:63], v[90:91] op_sel_hi:[1,0,1]
	ds_read_b128 v[64:67], v126 offset:576
	v_mov_b32_e32 v62, v63
	v_pk_fma_f32 v[88:89], v[58:59], v[62:63], v[92:93] op_sel_hi:[1,0,1]
	v_pk_fma_f32 v[90:91], v[56:57], v[62:63], v[94:95] op_sel_hi:[1,0,1]
	ds_read_b128 v[56:59], v126 offset:592
	s_waitcnt lgkmcnt(1)
	v_mov_b32_e32 v62, v67
	s_waitcnt vmcnt(13)
	v_pk_fma_f32 v[92:93], v[54:55], v[64:65], v[96:97] op_sel_hi:[1,0,1]
	v_pk_fma_f32 v[94:95], v[52:53], v[64:65], v[98:99] op_sel_hi:[1,0,1]
	v_pk_fma_f32 v[96:97], v[54:55], v[64:65], v[100:101] op_sel:[0,1,0]
	v_pk_fma_f32 v[64:65], v[52:53], v[64:65], v[68:69] op_sel:[0,1,0]
	v_pk_fma_f32 v[68:69], v[54:55], v[66:67], v[72:73] op_sel_hi:[1,0,1]
	v_pk_fma_f32 v[72:73], v[52:53], v[66:67], v[76:77] op_sel_hi:[1,0,1]
	v_pk_fma_f32 v[66:67], v[54:55], v[62:63], v[70:71] op_sel_hi:[1,0,1]
	v_pk_fma_f32 v[70:71], v[52:53], v[62:63], v[74:75] op_sel_hi:[1,0,1]
	s_waitcnt lgkmcnt(0)
	v_pk_fma_f32 v[74:75], v[54:55], v[56:57], v[78:79] op_sel_hi:[1,0,1]
	v_pk_fma_f32 v[76:77], v[52:53], v[56:57], v[80:81] op_sel_hi:[1,0,1]
	v_pk_fma_f32 v[78:79], v[54:55], v[56:57], v[82:83] op_sel:[0,1,0]
	v_pk_fma_f32 v[56:57], v[52:53], v[56:57], v[60:61] op_sel:[0,1,0]
	v_pk_fma_f32 v[80:81], v[54:55], v[58:59], v[84:85] op_sel_hi:[1,0,1]
	v_pk_fma_f32 v[82:83], v[52:53], v[58:59], v[86:87] op_sel_hi:[1,0,1]
	ds_read_b128 v[60:63], v126 offset:608
	v_mov_b32_e32 v58, v59
	v_pk_fma_f32 v[84:85], v[54:55], v[58:59], v[88:89] op_sel_hi:[1,0,1]
	v_pk_fma_f32 v[86:87], v[52:53], v[58:59], v[90:91] op_sel_hi:[1,0,1]
	ds_read_b128 v[52:55], v126 offset:624
	s_waitcnt lgkmcnt(1)
	v_mov_b32_e32 v58, v63
	s_waitcnt vmcnt(12)
	v_pk_fma_f32 v[88:89], v[50:51], v[60:61], v[92:93] op_sel_hi:[1,0,1]
	v_pk_fma_f32 v[90:91], v[48:49], v[60:61], v[94:95] op_sel_hi:[1,0,1]
	v_pk_fma_f32 v[92:93], v[50:51], v[60:61], v[96:97] op_sel:[0,1,0]
	v_pk_fma_f32 v[60:61], v[48:49], v[60:61], v[64:65] op_sel:[0,1,0]
	v_pk_fma_f32 v[64:65], v[50:51], v[62:63], v[68:69] op_sel_hi:[1,0,1]
	v_pk_fma_f32 v[68:69], v[48:49], v[62:63], v[72:73] op_sel_hi:[1,0,1]
	v_pk_fma_f32 v[62:63], v[50:51], v[58:59], v[66:67] op_sel_hi:[1,0,1]
	v_pk_fma_f32 v[66:67], v[48:49], v[58:59], v[70:71] op_sel_hi:[1,0,1]
	s_waitcnt lgkmcnt(0)
	v_pk_fma_f32 v[70:71], v[50:51], v[52:53], v[74:75] op_sel_hi:[1,0,1]
	v_pk_fma_f32 v[72:73], v[48:49], v[52:53], v[76:77] op_sel_hi:[1,0,1]
	v_pk_fma_f32 v[74:75], v[50:51], v[52:53], v[78:79] op_sel:[0,1,0]
	v_pk_fma_f32 v[52:53], v[48:49], v[52:53], v[56:57] op_sel:[0,1,0]
	v_pk_fma_f32 v[76:77], v[50:51], v[54:55], v[80:81] op_sel_hi:[1,0,1]
	v_pk_fma_f32 v[78:79], v[48:49], v[54:55], v[82:83] op_sel_hi:[1,0,1]
	ds_read_b128 v[56:59], v126 offset:640
	v_mov_b32_e32 v54, v55
	v_pk_fma_f32 v[80:81], v[50:51], v[54:55], v[84:85] op_sel_hi:[1,0,1]
	v_pk_fma_f32 v[82:83], v[48:49], v[54:55], v[86:87] op_sel_hi:[1,0,1]
	ds_read_b128 v[48:51], v126 offset:656
	s_waitcnt lgkmcnt(1)
	v_mov_b32_e32 v54, v59
	s_waitcnt vmcnt(11)
	v_pk_fma_f32 v[84:85], v[46:47], v[56:57], v[88:89] op_sel_hi:[1,0,1]
	v_pk_fma_f32 v[86:87], v[44:45], v[56:57], v[90:91] op_sel_hi:[1,0,1]
	v_pk_fma_f32 v[88:89], v[46:47], v[56:57], v[92:93] op_sel:[0,1,0]
	v_pk_fma_f32 v[56:57], v[44:45], v[56:57], v[60:61] op_sel:[0,1,0]
	v_pk_fma_f32 v[60:61], v[46:47], v[58:59], v[64:65] op_sel_hi:[1,0,1]
	v_pk_fma_f32 v[64:65], v[44:45], v[58:59], v[68:69] op_sel_hi:[1,0,1]
	v_pk_fma_f32 v[58:59], v[46:47], v[54:55], v[62:63] op_sel_hi:[1,0,1]
	v_pk_fma_f32 v[62:63], v[44:45], v[54:55], v[66:67] op_sel_hi:[1,0,1]
	s_waitcnt lgkmcnt(0)
	v_pk_fma_f32 v[66:67], v[46:47], v[48:49], v[70:71] op_sel_hi:[1,0,1]
	v_pk_fma_f32 v[68:69], v[44:45], v[48:49], v[72:73] op_sel_hi:[1,0,1]
	v_pk_fma_f32 v[70:71], v[46:47], v[48:49], v[74:75] op_sel:[0,1,0]
	v_pk_fma_f32 v[48:49], v[44:45], v[48:49], v[52:53] op_sel:[0,1,0]
	v_pk_fma_f32 v[72:73], v[46:47], v[50:51], v[76:77] op_sel_hi:[1,0,1]
	v_pk_fma_f32 v[74:75], v[44:45], v[50:51], v[78:79] op_sel_hi:[1,0,1]
	ds_read_b128 v[52:55], v126 offset:672
	v_mov_b32_e32 v50, v51
	v_pk_fma_f32 v[76:77], v[46:47], v[50:51], v[80:81] op_sel_hi:[1,0,1]
	v_pk_fma_f32 v[78:79], v[44:45], v[50:51], v[82:83] op_sel_hi:[1,0,1]
	ds_read_b128 v[44:47], v126 offset:688
	s_waitcnt lgkmcnt(1)
	v_mov_b32_e32 v50, v55
	s_waitcnt vmcnt(10)
	v_pk_fma_f32 v[80:81], v[42:43], v[52:53], v[84:85] op_sel_hi:[1,0,1]
	v_pk_fma_f32 v[82:83], v[40:41], v[52:53], v[86:87] op_sel_hi:[1,0,1]
	v_pk_fma_f32 v[84:85], v[42:43], v[52:53], v[88:89] op_sel:[0,1,0]
	v_pk_fma_f32 v[52:53], v[40:41], v[52:53], v[56:57] op_sel:[0,1,0]
	v_pk_fma_f32 v[56:57], v[42:43], v[54:55], v[60:61] op_sel_hi:[1,0,1]
	v_pk_fma_f32 v[60:61], v[40:41], v[54:55], v[64:65] op_sel_hi:[1,0,1]
	v_pk_fma_f32 v[54:55], v[42:43], v[50:51], v[58:59] op_sel_hi:[1,0,1]
	v_pk_fma_f32 v[58:59], v[40:41], v[50:51], v[62:63] op_sel_hi:[1,0,1]
	s_waitcnt lgkmcnt(0)
	v_pk_fma_f32 v[62:63], v[42:43], v[44:45], v[66:67] op_sel_hi:[1,0,1]
	v_pk_fma_f32 v[64:65], v[40:41], v[44:45], v[68:69] op_sel_hi:[1,0,1]
	v_pk_fma_f32 v[66:67], v[42:43], v[44:45], v[70:71] op_sel:[0,1,0]
	v_pk_fma_f32 v[44:45], v[40:41], v[44:45], v[48:49] op_sel:[0,1,0]
	v_pk_fma_f32 v[68:69], v[42:43], v[46:47], v[72:73] op_sel_hi:[1,0,1]
	v_pk_fma_f32 v[70:71], v[40:41], v[46:47], v[74:75] op_sel_hi:[1,0,1]
	ds_read_b128 v[48:51], v126 offset:704
	v_mov_b32_e32 v46, v47
	v_pk_fma_f32 v[72:73], v[42:43], v[46:47], v[76:77] op_sel_hi:[1,0,1]
	v_pk_fma_f32 v[74:75], v[40:41], v[46:47], v[78:79] op_sel_hi:[1,0,1]
	ds_read_b128 v[40:43], v126 offset:720
	s_waitcnt lgkmcnt(1)
	v_mov_b32_e32 v46, v51
	s_waitcnt vmcnt(9)
	v_pk_fma_f32 v[76:77], v[38:39], v[48:49], v[80:81] op_sel_hi:[1,0,1]
	v_pk_fma_f32 v[78:79], v[36:37], v[48:49], v[82:83] op_sel_hi:[1,0,1]
	v_pk_fma_f32 v[80:81], v[38:39], v[48:49], v[84:85] op_sel:[0,1,0]
	v_pk_fma_f32 v[48:49], v[36:37], v[48:49], v[52:53] op_sel:[0,1,0]
	v_pk_fma_f32 v[52:53], v[38:39], v[50:51], v[56:57] op_sel_hi:[1,0,1]
	v_pk_fma_f32 v[56:57], v[36:37], v[50:51], v[60:61] op_sel_hi:[1,0,1]
	v_pk_fma_f32 v[50:51], v[38:39], v[46:47], v[54:55] op_sel_hi:[1,0,1]
	v_pk_fma_f32 v[54:55], v[36:37], v[46:47], v[58:59] op_sel_hi:[1,0,1]
	s_waitcnt lgkmcnt(0)
	v_pk_fma_f32 v[58:59], v[38:39], v[40:41], v[62:63] op_sel_hi:[1,0,1]
	v_pk_fma_f32 v[60:61], v[36:37], v[40:41], v[64:65] op_sel_hi:[1,0,1]
	v_pk_fma_f32 v[62:63], v[38:39], v[40:41], v[66:67] op_sel:[0,1,0]
	v_pk_fma_f32 v[40:41], v[36:37], v[40:41], v[44:45] op_sel:[0,1,0]
	v_pk_fma_f32 v[64:65], v[38:39], v[42:43], v[68:69] op_sel_hi:[1,0,1]
	v_pk_fma_f32 v[66:67], v[36:37], v[42:43], v[70:71] op_sel_hi:[1,0,1]
	ds_read_b128 v[44:47], v126 offset:736
	v_mov_b32_e32 v42, v43
	v_pk_fma_f32 v[68:69], v[38:39], v[42:43], v[72:73] op_sel_hi:[1,0,1]
	v_pk_fma_f32 v[70:71], v[36:37], v[42:43], v[74:75] op_sel_hi:[1,0,1]
	ds_read_b128 v[36:39], v126 offset:752
	s_waitcnt lgkmcnt(1)
	v_mov_b32_e32 v42, v47
	s_waitcnt vmcnt(8)
	v_pk_fma_f32 v[72:73], v[34:35], v[44:45], v[76:77] op_sel_hi:[1,0,1]
	v_pk_fma_f32 v[74:75], v[32:33], v[44:45], v[78:79] op_sel_hi:[1,0,1]
	v_pk_fma_f32 v[76:77], v[34:35], v[44:45], v[80:81] op_sel:[0,1,0]
	v_pk_fma_f32 v[44:45], v[32:33], v[44:45], v[48:49] op_sel:[0,1,0]
	v_pk_fma_f32 v[48:49], v[34:35], v[46:47], v[52:53] op_sel_hi:[1,0,1]
	v_pk_fma_f32 v[52:53], v[32:33], v[46:47], v[56:57] op_sel_hi:[1,0,1]
	v_pk_fma_f32 v[46:47], v[34:35], v[42:43], v[50:51] op_sel_hi:[1,0,1]
	v_pk_fma_f32 v[50:51], v[32:33], v[42:43], v[54:55] op_sel_hi:[1,0,1]
	s_waitcnt lgkmcnt(0)
	v_pk_fma_f32 v[54:55], v[34:35], v[36:37], v[58:59] op_sel_hi:[1,0,1]
	v_pk_fma_f32 v[56:57], v[32:33], v[36:37], v[60:61] op_sel_hi:[1,0,1]
	v_pk_fma_f32 v[58:59], v[34:35], v[36:37], v[62:63] op_sel:[0,1,0]
	v_pk_fma_f32 v[36:37], v[32:33], v[36:37], v[40:41] op_sel:[0,1,0]
	v_pk_fma_f32 v[60:61], v[34:35], v[38:39], v[64:65] op_sel_hi:[1,0,1]
	v_pk_fma_f32 v[62:63], v[32:33], v[38:39], v[66:67] op_sel_hi:[1,0,1]
	ds_read_b128 v[40:43], v126 offset:768
	v_mov_b32_e32 v38, v39
	v_pk_fma_f32 v[64:65], v[34:35], v[38:39], v[68:69] op_sel_hi:[1,0,1]
	v_pk_fma_f32 v[66:67], v[32:33], v[38:39], v[70:71] op_sel_hi:[1,0,1]
	ds_read_b128 v[32:35], v126 offset:784
	s_waitcnt lgkmcnt(1)
	v_mov_b32_e32 v38, v43
	s_waitcnt vmcnt(7)
	v_pk_fma_f32 v[68:69], v[30:31], v[40:41], v[72:73] op_sel_hi:[1,0,1]
	v_pk_fma_f32 v[70:71], v[28:29], v[40:41], v[74:75] op_sel_hi:[1,0,1]
	v_pk_fma_f32 v[72:73], v[30:31], v[40:41], v[76:77] op_sel:[0,1,0]
	v_pk_fma_f32 v[40:41], v[28:29], v[40:41], v[44:45] op_sel:[0,1,0]
	v_pk_fma_f32 v[44:45], v[30:31], v[42:43], v[48:49] op_sel_hi:[1,0,1]
	v_pk_fma_f32 v[48:49], v[28:29], v[42:43], v[52:53] op_sel_hi:[1,0,1]
	v_pk_fma_f32 v[42:43], v[30:31], v[38:39], v[46:47] op_sel_hi:[1,0,1]
	v_pk_fma_f32 v[46:47], v[28:29], v[38:39], v[50:51] op_sel_hi:[1,0,1]
	s_waitcnt lgkmcnt(0)
	v_pk_fma_f32 v[50:51], v[30:31], v[32:33], v[54:55] op_sel_hi:[1,0,1]
	v_pk_fma_f32 v[52:53], v[28:29], v[32:33], v[56:57] op_sel_hi:[1,0,1]
	v_pk_fma_f32 v[54:55], v[30:31], v[32:33], v[58:59] op_sel:[0,1,0]
	v_pk_fma_f32 v[32:33], v[28:29], v[32:33], v[36:37] op_sel:[0,1,0]
	v_pk_fma_f32 v[56:57], v[30:31], v[34:35], v[60:61] op_sel_hi:[1,0,1]
	v_pk_fma_f32 v[58:59], v[28:29], v[34:35], v[62:63] op_sel_hi:[1,0,1]
	ds_read_b128 v[36:39], v126 offset:800
	v_mov_b32_e32 v34, v35
	v_pk_fma_f32 v[60:61], v[30:31], v[34:35], v[64:65] op_sel_hi:[1,0,1]
	v_pk_fma_f32 v[62:63], v[28:29], v[34:35], v[66:67] op_sel_hi:[1,0,1]
	ds_read_b128 v[28:31], v126 offset:816
	s_waitcnt lgkmcnt(1)
	v_mov_b32_e32 v34, v39
	s_waitcnt vmcnt(6)
	v_pk_fma_f32 v[64:65], v[26:27], v[36:37], v[68:69] op_sel_hi:[1,0,1]
	v_pk_fma_f32 v[66:67], v[24:25], v[36:37], v[70:71] op_sel_hi:[1,0,1]
	v_pk_fma_f32 v[68:69], v[26:27], v[36:37], v[72:73] op_sel:[0,1,0]
	v_pk_fma_f32 v[36:37], v[24:25], v[36:37], v[40:41] op_sel:[0,1,0]
	v_pk_fma_f32 v[40:41], v[26:27], v[38:39], v[44:45] op_sel_hi:[1,0,1]
	v_pk_fma_f32 v[44:45], v[24:25], v[38:39], v[48:49] op_sel_hi:[1,0,1]
	v_pk_fma_f32 v[38:39], v[26:27], v[34:35], v[42:43] op_sel_hi:[1,0,1]
	v_pk_fma_f32 v[42:43], v[24:25], v[34:35], v[46:47] op_sel_hi:[1,0,1]
	s_waitcnt lgkmcnt(0)
	v_pk_fma_f32 v[46:47], v[26:27], v[28:29], v[50:51] op_sel_hi:[1,0,1]
	v_pk_fma_f32 v[48:49], v[24:25], v[28:29], v[52:53] op_sel_hi:[1,0,1]
	v_pk_fma_f32 v[50:51], v[26:27], v[28:29], v[54:55] op_sel:[0,1,0]
	v_pk_fma_f32 v[28:29], v[24:25], v[28:29], v[32:33] op_sel:[0,1,0]
	v_pk_fma_f32 v[52:53], v[26:27], v[30:31], v[56:57] op_sel_hi:[1,0,1]
	v_pk_fma_f32 v[54:55], v[24:25], v[30:31], v[58:59] op_sel_hi:[1,0,1]
	ds_read_b128 v[32:35], v126 offset:832
	v_mov_b32_e32 v30, v31
	v_pk_fma_f32 v[56:57], v[26:27], v[30:31], v[60:61] op_sel_hi:[1,0,1]
	v_pk_fma_f32 v[58:59], v[24:25], v[30:31], v[62:63] op_sel_hi:[1,0,1]
	ds_read_b128 v[24:27], v126 offset:848
	s_waitcnt lgkmcnt(1)
	v_mov_b32_e32 v30, v35
	s_waitcnt vmcnt(5)
	v_pk_fma_f32 v[60:61], v[22:23], v[32:33], v[64:65] op_sel_hi:[1,0,1]
	v_pk_fma_f32 v[62:63], v[20:21], v[32:33], v[66:67] op_sel_hi:[1,0,1]
	v_pk_fma_f32 v[64:65], v[22:23], v[32:33], v[68:69] op_sel:[0,1,0]
	v_pk_fma_f32 v[32:33], v[20:21], v[32:33], v[36:37] op_sel:[0,1,0]
	v_pk_fma_f32 v[36:37], v[22:23], v[34:35], v[40:41] op_sel_hi:[1,0,1]
	v_pk_fma_f32 v[40:41], v[20:21], v[34:35], v[44:45] op_sel_hi:[1,0,1]
	v_pk_fma_f32 v[34:35], v[22:23], v[30:31], v[38:39] op_sel_hi:[1,0,1]
	v_pk_fma_f32 v[38:39], v[20:21], v[30:31], v[42:43] op_sel_hi:[1,0,1]
	s_waitcnt lgkmcnt(0)
	v_pk_fma_f32 v[42:43], v[22:23], v[24:25], v[46:47] op_sel_hi:[1,0,1]
	v_pk_fma_f32 v[44:45], v[20:21], v[24:25], v[48:49] op_sel_hi:[1,0,1]
	v_pk_fma_f32 v[46:47], v[22:23], v[24:25], v[50:51] op_sel:[0,1,0]
	v_pk_fma_f32 v[24:25], v[20:21], v[24:25], v[28:29] op_sel:[0,1,0]
	v_pk_fma_f32 v[48:49], v[22:23], v[26:27], v[52:53] op_sel_hi:[1,0,1]
	v_pk_fma_f32 v[50:51], v[20:21], v[26:27], v[54:55] op_sel_hi:[1,0,1]
	ds_read_b128 v[28:31], v126 offset:864
	v_mov_b32_e32 v26, v27
	v_pk_fma_f32 v[52:53], v[22:23], v[26:27], v[56:57] op_sel_hi:[1,0,1]
	v_pk_fma_f32 v[54:55], v[20:21], v[26:27], v[58:59] op_sel_hi:[1,0,1]
	ds_read_b128 v[20:23], v126 offset:880
	s_waitcnt lgkmcnt(1)
	v_mov_b32_e32 v26, v31
	s_waitcnt vmcnt(4)
	v_pk_fma_f32 v[56:57], v[18:19], v[28:29], v[60:61] op_sel_hi:[1,0,1]
	v_pk_fma_f32 v[58:59], v[16:17], v[28:29], v[62:63] op_sel_hi:[1,0,1]
	v_pk_fma_f32 v[60:61], v[18:19], v[28:29], v[64:65] op_sel:[0,1,0]
	v_pk_fma_f32 v[28:29], v[16:17], v[28:29], v[32:33] op_sel:[0,1,0]
	v_pk_fma_f32 v[32:33], v[18:19], v[30:31], v[36:37] op_sel_hi:[1,0,1]
	v_pk_fma_f32 v[36:37], v[16:17], v[30:31], v[40:41] op_sel_hi:[1,0,1]
	v_pk_fma_f32 v[30:31], v[18:19], v[26:27], v[34:35] op_sel_hi:[1,0,1]
	v_pk_fma_f32 v[34:35], v[16:17], v[26:27], v[38:39] op_sel_hi:[1,0,1]
	s_waitcnt lgkmcnt(0)
	v_pk_fma_f32 v[38:39], v[18:19], v[20:21], v[42:43] op_sel_hi:[1,0,1]
	v_pk_fma_f32 v[40:41], v[16:17], v[20:21], v[44:45] op_sel_hi:[1,0,1]
	v_pk_fma_f32 v[42:43], v[18:19], v[20:21], v[46:47] op_sel:[0,1,0]
	v_pk_fma_f32 v[20:21], v[16:17], v[20:21], v[24:25] op_sel:[0,1,0]
	v_pk_fma_f32 v[44:45], v[18:19], v[22:23], v[48:49] op_sel_hi:[1,0,1]
	v_pk_fma_f32 v[46:47], v[16:17], v[22:23], v[50:51] op_sel_hi:[1,0,1]
	ds_read_b128 v[24:27], v126 offset:896
	v_mov_b32_e32 v22, v23
	v_pk_fma_f32 v[48:49], v[18:19], v[22:23], v[52:53] op_sel_hi:[1,0,1]
	v_pk_fma_f32 v[50:51], v[16:17], v[22:23], v[54:55] op_sel_hi:[1,0,1]
	ds_read_b128 v[16:19], v126 offset:912
	s_waitcnt lgkmcnt(1)
	v_mov_b32_e32 v22, v27
	s_waitcnt vmcnt(3)
	v_pk_fma_f32 v[52:53], v[14:15], v[24:25], v[56:57] op_sel_hi:[1,0,1]
	v_pk_fma_f32 v[54:55], v[12:13], v[24:25], v[58:59] op_sel_hi:[1,0,1]
	v_pk_fma_f32 v[56:57], v[14:15], v[24:25], v[60:61] op_sel:[0,1,0]
	v_pk_fma_f32 v[24:25], v[12:13], v[24:25], v[28:29] op_sel:[0,1,0]
	v_pk_fma_f32 v[28:29], v[14:15], v[26:27], v[32:33] op_sel_hi:[1,0,1]
	v_pk_fma_f32 v[32:33], v[12:13], v[26:27], v[36:37] op_sel_hi:[1,0,1]
	v_pk_fma_f32 v[26:27], v[14:15], v[22:23], v[30:31] op_sel_hi:[1,0,1]
	v_pk_fma_f32 v[30:31], v[12:13], v[22:23], v[34:35] op_sel_hi:[1,0,1]
	s_waitcnt lgkmcnt(0)
	v_pk_fma_f32 v[34:35], v[14:15], v[16:17], v[38:39] op_sel_hi:[1,0,1]
	v_pk_fma_f32 v[36:37], v[12:13], v[16:17], v[40:41] op_sel_hi:[1,0,1]
	v_pk_fma_f32 v[38:39], v[14:15], v[16:17], v[42:43] op_sel:[0,1,0]
	v_pk_fma_f32 v[16:17], v[12:13], v[16:17], v[20:21] op_sel:[0,1,0]
	v_pk_fma_f32 v[40:41], v[14:15], v[18:19], v[44:45] op_sel_hi:[1,0,1]
	v_pk_fma_f32 v[42:43], v[12:13], v[18:19], v[46:47] op_sel_hi:[1,0,1]
	ds_read_b128 v[20:23], v126 offset:928
	v_mov_b32_e32 v18, v19
	v_pk_fma_f32 v[44:45], v[14:15], v[18:19], v[48:49] op_sel_hi:[1,0,1]
	v_pk_fma_f32 v[46:47], v[12:13], v[18:19], v[50:51] op_sel_hi:[1,0,1]
	ds_read_b128 v[12:15], v126 offset:944
	s_waitcnt lgkmcnt(1)
	v_mov_b32_e32 v18, v23
	s_waitcnt vmcnt(2)
	v_pk_fma_f32 v[48:49], v[10:11], v[20:21], v[52:53] op_sel_hi:[1,0,1]
	v_pk_fma_f32 v[50:51], v[8:9], v[20:21], v[54:55] op_sel_hi:[1,0,1]
	v_pk_fma_f32 v[52:53], v[10:11], v[20:21], v[56:57] op_sel:[0,1,0]
	v_pk_fma_f32 v[20:21], v[8:9], v[20:21], v[24:25] op_sel:[0,1,0]
	v_pk_fma_f32 v[24:25], v[10:11], v[22:23], v[28:29] op_sel_hi:[1,0,1]
	v_pk_fma_f32 v[28:29], v[8:9], v[22:23], v[32:33] op_sel_hi:[1,0,1]
	v_pk_fma_f32 v[22:23], v[10:11], v[18:19], v[26:27] op_sel_hi:[1,0,1]
	v_pk_fma_f32 v[26:27], v[8:9], v[18:19], v[30:31] op_sel_hi:[1,0,1]
	s_waitcnt lgkmcnt(0)
	v_pk_fma_f32 v[30:31], v[10:11], v[12:13], v[34:35] op_sel_hi:[1,0,1]
	v_pk_fma_f32 v[32:33], v[8:9], v[12:13], v[36:37] op_sel_hi:[1,0,1]
	v_pk_fma_f32 v[34:35], v[10:11], v[12:13], v[38:39] op_sel:[0,1,0]
	v_pk_fma_f32 v[12:13], v[8:9], v[12:13], v[16:17] op_sel:[0,1,0]
	v_pk_fma_f32 v[36:37], v[10:11], v[14:15], v[40:41] op_sel_hi:[1,0,1]
	v_pk_fma_f32 v[38:39], v[8:9], v[14:15], v[42:43] op_sel_hi:[1,0,1]
	ds_read_b128 v[16:19], v126 offset:960
	v_mov_b32_e32 v14, v15
	v_pk_fma_f32 v[40:41], v[10:11], v[14:15], v[44:45] op_sel_hi:[1,0,1]
	v_pk_fma_f32 v[42:43], v[8:9], v[14:15], v[46:47] op_sel_hi:[1,0,1]
	ds_read_b128 v[8:11], v126 offset:976
	s_waitcnt lgkmcnt(1)
	v_mov_b32_e32 v14, v19
	s_waitcnt vmcnt(1)
	v_pk_fma_f32 v[44:45], v[6:7], v[16:17], v[48:49] op_sel_hi:[1,0,1]
	v_pk_fma_f32 v[46:47], v[4:5], v[16:17], v[50:51] op_sel_hi:[1,0,1]
	v_pk_fma_f32 v[48:49], v[6:7], v[16:17], v[52:53] op_sel:[0,1,0]
	v_pk_fma_f32 v[16:17], v[4:5], v[16:17], v[20:21] op_sel:[0,1,0]
	v_pk_fma_f32 v[20:21], v[6:7], v[18:19], v[24:25] op_sel_hi:[1,0,1]
	v_pk_fma_f32 v[24:25], v[4:5], v[18:19], v[28:29] op_sel_hi:[1,0,1]
	v_pk_fma_f32 v[28:29], v[6:7], v[14:15], v[22:23] op_sel_hi:[1,0,1]
	v_pk_fma_f32 v[26:27], v[4:5], v[14:15], v[26:27] op_sel_hi:[1,0,1]
	s_waitcnt lgkmcnt(0)
	v_pk_fma_f32 v[30:31], v[6:7], v[8:9], v[30:31] op_sel_hi:[1,0,1]
	v_pk_fma_f32 v[32:33], v[4:5], v[8:9], v[32:33] op_sel_hi:[1,0,1]
	v_pk_fma_f32 v[34:35], v[6:7], v[8:9], v[34:35] op_sel:[0,1,0]
	v_pk_fma_f32 v[50:51], v[4:5], v[8:9], v[12:13] op_sel:[0,1,0]
	ds_read_b128 v[12:15], v126 offset:992
	v_mov_b32_e32 v8, v11
	v_pk_fma_f32 v[36:37], v[6:7], v[10:11], v[36:37] op_sel_hi:[1,0,1]
	v_pk_fma_f32 v[38:39], v[4:5], v[10:11], v[38:39] op_sel_hi:[1,0,1]
	v_pk_fma_f32 v[40:41], v[6:7], v[8:9], v[40:41] op_sel_hi:[1,0,1]
	v_pk_fma_f32 v[42:43], v[4:5], v[8:9], v[42:43] op_sel_hi:[1,0,1]
	ds_read_b128 v[4:7], v126 offset:1008
	s_waitcnt vmcnt(0) lgkmcnt(1)
	v_pk_fma_f32 v[10:11], v[2:3], v[12:13], v[44:45] op_sel_hi:[1,0,1]
	v_pk_fma_f32 v[8:9], v[0:1], v[12:13], v[46:47] op_sel_hi:[1,0,1]
	v_pk_fma_f32 v[18:19], v[2:3], v[12:13], v[48:49] op_sel:[0,1,0]
	v_pk_fma_f32 v[16:17], v[0:1], v[12:13], v[16:17] op_sel:[0,1,0]
	v_mov_b32_e32 v12, v15
	v_pk_fma_f32 v[22:23], v[2:3], v[14:15], v[20:21] op_sel_hi:[1,0,1]
	v_pk_fma_f32 v[20:21], v[0:1], v[14:15], v[24:25] op_sel_hi:[1,0,1]
	v_pk_fma_f32 v[14:15], v[2:3], v[12:13], v[28:29] op_sel_hi:[1,0,1]
	v_pk_fma_f32 v[12:13], v[0:1], v[12:13], v[26:27] op_sel_hi:[1,0,1]
	s_waitcnt lgkmcnt(0)
	v_pk_fma_f32 v[26:27], v[2:3], v[4:5], v[30:31] op_sel_hi:[1,0,1]
	v_pk_fma_f32 v[24:25], v[0:1], v[4:5], v[32:33] op_sel_hi:[1,0,1]
	v_pk_fma_f32 v[30:31], v[2:3], v[4:5], v[34:35] op_sel:[0,1,0]
	v_pk_fma_f32 v[28:29], v[0:1], v[4:5], v[50:51] op_sel:[0,1,0]
	v_mov_b32_e32 v4, v7
	v_pk_fma_f32 v[34:35], v[2:3], v[6:7], v[36:37] op_sel_hi:[1,0,1]
	v_pk_fma_f32 v[32:33], v[0:1], v[6:7], v[38:39] op_sel_hi:[1,0,1]
	v_pk_fma_f32 v[2:3], v[2:3], v[4:5], v[40:41] op_sel_hi:[1,0,1]
	v_pk_fma_f32 v[0:1], v[0:1], v[4:5], v[42:43] op_sel_hi:[1,0,1]
	v_lshlrev_b32_e32 v4, 13, v124
	v_add3_u32 v4, 0, v4, v192
	ds_write_b128 v4, v[8:11] offset:8192
	ds_write_b128 v4, v[16:19] offset:9216
	ds_write_b128 v4, v[20:23] offset:10240
	ds_write_b128 v4, v[12:15] offset:11264
	ds_write_b128 v4, v[24:27] offset:12288
	ds_write_b128 v4, v[28:31] offset:13312
	ds_write_b128 v4, v[32:35] offset:14336
	ds_write_b128 v4, v[0:3] offset:15360
	v_add_u32_e32 v20, v126, v192
	s_waitcnt lgkmcnt(0)
	s_barrier
	ds_read_b128 v[0:3], v20 offset:8192
	ds_read_b128 v[4:7], v20 offset:16384
	v_add_u32_e32 v16, 0x2000, v20
	v_lshlrev_b32_e32 v192, 3, v125
	s_waitcnt lgkmcnt(1)
	v_pk_add_f32 v[8:9], v[2:3], 0 op_sel_hi:[1,0]
	v_pk_add_f32 v[10:11], v[0:1], 0 op_sel_hi:[1,0]
	ds_read_b128 v[0:3], v20 offset:24576
	s_waitcnt lgkmcnt(1)
	v_pk_add_f32 v[12:13], v[8:9], v[6:7]
	v_pk_add_f32 v[14:15], v[10:11], v[4:5]
	ds_read_b128 v[4:7], v20 offset:32768
	ds_read_b128 v[8:11], v16 offset:57344
	s_waitcnt lgkmcnt(2)
	v_pk_add_f32 v[12:13], v[12:13], v[2:3]
	v_pk_add_f32 v[16:17], v[14:15], v[0:1]
	ds_read_b128 v[0:3], v20 offset:40960
	s_waitcnt lgkmcnt(2)
	v_pk_add_f32 v[18:19], v[12:13], v[6:7]
	ds_read_b128 v[12:15], v20 offset:49152
	v_pk_add_f32 v[16:17], v[16:17], v[4:5]
	ds_read_b128 v[4:7], v20 offset:57344
	s_waitcnt lgkmcnt(2)
	v_pk_add_f32 v[0:1], v[16:17], v[0:1]
	v_pk_add_f32 v[2:3], v[18:19], v[2:3]
	s_waitcnt lgkmcnt(1)
	v_pk_add_f32 v[0:1], v[0:1], v[12:13]
	v_pk_add_f32 v[2:3], v[2:3], v[14:15]
	s_waitcnt lgkmcnt(0)
	v_pk_add_f32 v[0:1], v[0:1], v[4:5]
	v_add_u32_e32 v4, s26, v124
	v_ashrrev_i32_e32 v5, 31, v4
	v_lshlrev_b64 v[4:5], 11, v[4:5]
	v_pk_add_f32 v[2:3], v[2:3], v[6:7]
	v_lshl_add_u64 v[4:5], s[4:5], 0, v[4:5]
	v_lshl_add_u64 v[4:5], v[4:5], 0, s[82:83]
	v_pk_add_f32 v[2:3], v[2:3], v[10:11]
	v_pk_add_f32 v[0:1], v[0:1], v[8:9]
	v_lshl_add_u64 v[4:5], v[4:5], 0, v[192:193]
	v_cvt_pk_bf16_f32 v0, v0, v1
	v_cvt_pk_bf16_f32 v1, v2, v3
	v_add_co_u32_e32 v2, vcc, 0x11e00000, v4
	s_nop 1
	v_addc_co_u32_e32 v3, vcc, 0, v5, vcc
	global_store_dwordx2 v[2:3], v[0:1], off
	s_waitcnt lgkmcnt(0)
	s_barrier
	s_cbranch_scc1 .LBB0_43
